# FoxProj f32 k/v output stores and FFN-down partial-tile stores routed through the per-wave LDS transpose (whole 128-B row segments per 8 adjacent lanes)
# speedup vs baseline: 1.0505x; 1.0123x over previous
;     __device__ __forceinline__ void operator()(const pg8::f32x4 (&acc)[2][2][4][2], const pg8::Unit& u, int wr, int wc, int fr, int fq) const {
; #pragma unroll
;         for (int ai = 0; ai < 2; ++ai)
; #pragma unroll
;             for (int m = 0; m < 4; ++m) { float* rowp = part + (size_t)(ai * 128 + wr * 64 + m * 16 + fr) * 256 + wc * 32 + 8 * fq;
; #pragma unroll
;                 for (int bj = 0; bj < 2; ++bj) { *(f32x4*)(rowp + bj * 128) = acc[ai][bj][m][0]; *(f32x4*)(rowp + bj * 128 + 4) = acc[ai][bj][m][1]; } }
.LBB0_1200:
	s_add_u32 s0, s28, 0x25e00000
	s_addc_u32 s1, s29, 0
	s_ashr_i32 s3, s2, 31
	s_lshl_b64 s[4:5], s[2:3], 18
	v_mov_b32_e32 v131, 0
	s_add_u32 s4, s0, s4
	v_add_u32_e32 v130, 0xb0, v138
	v_add_u32_e32 v134, 0xa0, v138
	v_mov_b32_e32 v135, v131
	v_add_u32_e32 v136, 0x90, v138
	v_mov_b32_e32 v137, v131
	v_add_u32_e32 v140, 0x80, v138
	v_mov_b32_e32 v141, v131
	v_or_b32_e32 v142, 48, v138
	v_mov_b32_e32 v143, v131
	v_or_b32_e32 v144, 32, v138
	v_mov_b32_e32 v145, v131
	v_or_b32_e32 v146, 16, v138
	v_mov_b32_e32 v147, v131
	v_mov_b32_e32 v139, v131
	s_addc_u32 s5, s1, s5
	v_lshlrev_b64 v[132:133], 10, v[130:131]
	v_lshlrev_b64 v[134:135], 10, v[134:135]
	v_lshlrev_b64 v[136:137], 10, v[136:137]
	v_lshlrev_b64 v[140:141], 10, v[140:141]
	v_lshlrev_b64 v[142:143], 10, v[142:143]
	v_lshlrev_b64 v[144:145], 10, v[144:145]
	v_lshlrev_b64 v[146:147], 10, v[146:147]
	v_lshlrev_b64 v[138:139], 10, v[138:139]
	s_mov_b32 s7, 0
	v_lshl_add_u64 v[132:133], s[4:5], 0, v[132:133]
	s_lshl_b32 s6, s39, 2
	v_lshl_add_u64 v[134:135], s[4:5], 0, v[134:135]
	v_lshl_add_u64 v[136:137], s[4:5], 0, v[136:137]
	v_lshl_add_u64 v[140:141], s[4:5], 0, v[140:141]
	v_lshl_add_u64 v[142:143], s[4:5], 0, v[142:143]
	v_lshl_add_u64 v[144:145], s[4:5], 0, v[144:145]
	v_lshl_add_u64 v[146:147], s[4:5], 0, v[146:147]
	v_lshl_add_u64 v[138:139], s[4:5], 0, v[138:139]
	v_lshl_add_u64 v[132:133], v[132:133], 0, s[6:7]
	v_lshlrev_b32_e32 v130, 2, v156
	v_lshl_add_u64 v[134:135], v[134:135], 0, s[6:7]
	v_lshl_add_u64 v[136:137], v[136:137], 0, s[6:7]
	v_lshl_add_u64 v[140:141], v[140:141], 0, s[6:7]
	v_lshl_add_u64 v[142:143], v[142:143], 0, s[6:7]
	v_lshl_add_u64 v[144:145], v[144:145], 0, s[6:7]
	v_lshl_add_u64 v[146:147], v[146:147], 0, s[6:7]
	v_lshl_add_u64 v[138:139], v[138:139], 0, s[6:7]
	v_lshl_add_u64 v[132:133], v[132:133], 0, v[130:131]
	v_lshl_add_u64 v[134:135], v[134:135], 0, v[130:131]
	v_lshl_add_u64 v[136:137], v[136:137], 0, v[130:131]
	v_lshl_add_u64 v[140:141], v[140:141], 0, v[130:131]
	v_lshl_add_u64 v[142:143], v[142:143], 0, v[130:131]
	v_lshl_add_u64 v[144:145], v[144:145], 0, v[130:131]
	v_lshl_add_u64 v[146:147], v[146:147], 0, v[130:131]
	v_lshl_add_u64 v[130:131], v[138:139], 0, v[130:131]
	v_and_b32_e32 v160, 63, v0
	v_and_b32_e32 v161, 15, v160
	v_lshrrev_b32_e32 v162, 4, v160
	v_lshrrev_b32_e32 v163, 3, v160
	v_and_b32_e32 v164, 7, v160
	v_lshrrev_b32_e32 v160, 6, v0
	v_mul_u32_u24_e32 v160, 0x900, v160
	v_add_u32_e32 v160, 0x21000, v160
	v_mul_u32_u24_e32 v150, 0x90, v161
	v_lshl_add_u32 v150, v162, 5, v150
	v_add_u32_e32 v158, v160, v150
	v_mul_u32_u24_e32 v150, 0x90, v163
	v_lshl_add_u32 v150, v164, 4, v150
	v_add_u32_e32 v159, v160, v150
	v_sub_u32_e32 v150, v163, v161
	v_lshlrev_b32_e32 v150, 10, v150
	v_lshl_add_u32 v150, v164, 4, v150
	v_lshlrev_b32_e32 v160, 5, v162
	v_sub_u32_e32 v138, v150, v160
	v_ashrrev_i32_e32 v139, 31, v138
	v_add_u32_e32 v148, 0x2000, v138
	v_ashrrev_i32_e32 v149, 31, v148
	ds_write_b128 v158, v[126:129]
	ds_write_b128 v158, v[122:125] offset:16
	ds_read_b128 v[126:129], v159
	ds_read_b128 v[122:125], v159 offset:1152
	ds_write_b128 v158, v[102:105]
	ds_write_b128 v158, v[94:97] offset:16
	ds_read_b128 v[102:105], v159
	ds_read_b128 v[94:97], v159 offset:1152
	s_waitcnt lgkmcnt(4)
	v_lshl_add_u64 v[150:151], v[130:131], 0, v[138:139]
	v_lshl_add_u64 v[152:153], v[130:131], 0, v[148:149]
	global_store_dwordx4 v[150:151], v[126:129], off
	global_store_dwordx4 v[152:153], v[122:125], off
	ds_write_b128 v158, v[118:121]
	ds_write_b128 v158, v[114:117] offset:16
	ds_read_b128 v[118:121], v159
	ds_read_b128 v[114:117], v159 offset:1152
	s_waitcnt lgkmcnt(4)
	v_lshl_add_u64 v[154:155], v[130:131], 0, v[138:139]
	v_lshl_add_u64 v[156:157], v[130:131], 0, v[148:149]
	global_store_dwordx4 v[154:155], v[102:105], off offset:512
	global_store_dwordx4 v[156:157], v[94:97], off offset:512
	ds_write_b128 v158, v[86:89]
	ds_write_b128 v158, v[82:85] offset:16
	ds_read_b128 v[86:89], v159
	ds_read_b128 v[82:85], v159 offset:1152
	s_waitcnt lgkmcnt(4)
	v_lshl_add_u64 v[150:151], v[146:147], 0, v[138:139]
	v_lshl_add_u64 v[152:153], v[146:147], 0, v[148:149]
	global_store_dwordx4 v[150:151], v[118:121], off
	global_store_dwordx4 v[152:153], v[114:117], off
	ds_write_b128 v158, v[110:113]
	ds_write_b128 v158, v[106:109] offset:16
	ds_read_b128 v[110:113], v159
	ds_read_b128 v[106:109], v159 offset:1152
	s_waitcnt lgkmcnt(4)
	v_lshl_add_u64 v[154:155], v[146:147], 0, v[138:139]
	v_lshl_add_u64 v[156:157], v[146:147], 0, v[148:149]
	global_store_dwordx4 v[154:155], v[86:89], off offset:512
	global_store_dwordx4 v[156:157], v[82:85], off offset:512
	ds_write_b128 v158, v[78:81]
	ds_write_b128 v158, v[74:77] offset:16
	ds_read_b128 v[78:81], v159
	ds_read_b128 v[74:77], v159 offset:1152
	s_waitcnt lgkmcnt(4)
	v_lshl_add_u64 v[150:151], v[144:145], 0, v[138:139]
	v_lshl_add_u64 v[152:153], v[144:145], 0, v[148:149]
	global_store_dwordx4 v[150:151], v[110:113], off
	global_store_dwordx4 v[152:153], v[106:109], off
	ds_write_b128 v158, v[98:101]
	ds_write_b128 v158, v[90:93] offset:16
	ds_read_b128 v[98:101], v159
	ds_read_b128 v[90:93], v159 offset:1152
	s_waitcnt lgkmcnt(4)
	v_lshl_add_u64 v[154:155], v[144:145], 0, v[138:139]
	v_lshl_add_u64 v[156:157], v[144:145], 0, v[148:149]
	global_store_dwordx4 v[154:155], v[78:81], off offset:512
	global_store_dwordx4 v[156:157], v[74:77], off offset:512
	ds_write_b128 v158, v[70:73]
	ds_write_b128 v158, v[66:69] offset:16
	ds_read_b128 v[70:73], v159
	ds_read_b128 v[66:69], v159 offset:1152
	s_waitcnt lgkmcnt(4)
; #define PG8_WAIT_V(n) asm volatile("s_waitcnt vmcnt(" #n ")" ::: "memory")
; #define PG8_BAR __builtin_amdgcn_s_barrier()
; template <class Epi, class Sched, bool ALIGN_EPI = false, bool SP2 = false>
; __device__ __forceinline__ void gemm_phase(PG8_LAS unsigned char* lds, const Gemm g, const Sched& S, const Epi& E) {
;     ...
;     PG8_WAIT_V(0);
;     if constexpr (!ALIGN_EPI) { if (wr == 0) PG8_BAR; }
;     PG8_BAR;
;     __device__ __forceinline__ void operator()(const pg8::f32x4 (&acc)[2][2][4][2], const pg8::Unit& u, int wr, int wc, int fr, int fq) const {
; #pragma unroll
;         for (int ai = 0; ai < 2; ++ai)
; #pragma unroll
;             for (int m = 0; m < 4; ++m) { float* rowp = part + (size_t)(ai * 128 + wr * 64 + m * 16 + fr) * 256 + wc * 32 + 8 * fq;
; #pragma unroll
;                 for (int bj = 0; bj < 2; ++bj) { *(f32x4*)(rowp + bj * 128) = acc[ai][bj][m][0]; *(f32x4*)(rowp + bj * 128 + 4) = acc[ai][bj][m][1]; } }
	v_lshl_add_u64 v[150:151], v[142:143], 0, v[138:139]
	v_lshl_add_u64 v[152:153], v[142:143], 0, v[148:149]
	global_store_dwordx4 v[150:151], v[98:101], off
	global_store_dwordx4 v[152:153], v[90:93], off
	ds_write_b128 v158, v[62:65]
	ds_write_b128 v158, v[58:61] offset:16
	ds_read_b128 v[62:65], v159
	ds_read_b128 v[58:61], v159 offset:1152
	s_waitcnt lgkmcnt(4)
	v_lshl_add_u64 v[154:155], v[142:143], 0, v[138:139]
	v_lshl_add_u64 v[156:157], v[142:143], 0, v[148:149]
	global_store_dwordx4 v[154:155], v[70:73], off offset:512
	global_store_dwordx4 v[156:157], v[66:69], off offset:512
	ds_write_b128 v158, v[38:41]
	ds_write_b128 v158, v[30:33] offset:16
	ds_read_b128 v[38:41], v159
	ds_read_b128 v[30:33], v159 offset:1152
	s_waitcnt lgkmcnt(4)
	v_lshl_add_u64 v[150:151], v[140:141], 0, v[138:139]
	v_lshl_add_u64 v[152:153], v[140:141], 0, v[148:149]
	global_store_dwordx4 v[150:151], v[62:65], off
	global_store_dwordx4 v[152:153], v[58:61], off
	ds_write_b128 v158, v[54:57]
	ds_write_b128 v158, v[50:53] offset:16
	ds_read_b128 v[54:57], v159
	ds_read_b128 v[50:53], v159 offset:1152
	s_waitcnt lgkmcnt(4)
	v_lshl_add_u64 v[154:155], v[140:141], 0, v[138:139]
	v_lshl_add_u64 v[156:157], v[140:141], 0, v[148:149]
	global_store_dwordx4 v[154:155], v[38:41], off offset:512
	global_store_dwordx4 v[156:157], v[30:33], off offset:512
	ds_write_b128 v158, v[22:25]
	ds_write_b128 v158, v[18:21] offset:16
	ds_read_b128 v[22:25], v159
	ds_read_b128 v[18:21], v159 offset:1152
	s_waitcnt lgkmcnt(4)
	v_lshl_add_u64 v[150:151], v[136:137], 0, v[138:139]
	v_lshl_add_u64 v[152:153], v[136:137], 0, v[148:149]
	global_store_dwordx4 v[150:151], v[54:57], off
	global_store_dwordx4 v[152:153], v[50:53], off
	ds_write_b128 v158, v[46:49]
	ds_write_b128 v158, v[42:45] offset:16
	ds_read_b128 v[46:49], v159
	ds_read_b128 v[42:45], v159 offset:1152
	s_waitcnt lgkmcnt(4)
	v_lshl_add_u64 v[154:155], v[136:137], 0, v[138:139]
	v_lshl_add_u64 v[156:157], v[136:137], 0, v[148:149]
	global_store_dwordx4 v[154:155], v[22:25], off offset:512
	global_store_dwordx4 v[156:157], v[18:21], off offset:512
	ds_write_b128 v158, v[14:17]
	ds_write_b128 v158, v[10:13] offset:16
	ds_read_b128 v[14:17], v159
	ds_read_b128 v[10:13], v159 offset:1152
	s_waitcnt lgkmcnt(4)
	v_lshl_add_u64 v[150:151], v[134:135], 0, v[138:139]
	v_lshl_add_u64 v[152:153], v[134:135], 0, v[148:149]
	global_store_dwordx4 v[150:151], v[46:49], off
	global_store_dwordx4 v[152:153], v[42:45], off
	ds_write_b128 v158, v[34:37]
	ds_write_b128 v158, v[26:29] offset:16
	ds_read_b128 v[34:37], v159
	ds_read_b128 v[26:29], v159 offset:1152
	s_waitcnt lgkmcnt(4)
	v_lshl_add_u64 v[154:155], v[134:135], 0, v[138:139]
	v_lshl_add_u64 v[156:157], v[134:135], 0, v[148:149]
	global_store_dwordx4 v[154:155], v[14:17], off offset:512
	global_store_dwordx4 v[156:157], v[10:13], off offset:512
	ds_write_b128 v158, v[6:9]
	ds_write_b128 v158, v[2:5] offset:16
	ds_read_b128 v[6:9], v159
	ds_read_b128 v[2:5], v159 offset:1152
	s_waitcnt lgkmcnt(4)
	v_lshl_add_u64 v[150:151], v[132:133], 0, v[138:139]
	v_lshl_add_u64 v[152:153], v[132:133], 0, v[148:149]
	global_store_dwordx4 v[150:151], v[34:37], off
	global_store_dwordx4 v[152:153], v[26:29], off
	s_waitcnt lgkmcnt(0)
	v_lshl_add_u64 v[154:155], v[132:133], 0, v[138:139]
	v_lshl_add_u64 v[156:157], v[132:133], 0, v[148:149]
	global_store_dwordx4 v[154:155], v[6:9], off offset:512
	global_store_dwordx4 v[156:157], v[2:5], off offset:512
	s_waitcnt vmcnt(0)
	s_barrier
	v_writelane_b32 v253, s0, 0
	v_writelane_b32 v253, s1, 1
	v_writelane_b32 v253, s3, 2
	v_writelane_b32 v253, s38, 3
	v_writelane_b32 v253, s39, 4
	v_writelane_b32 v253, s40, 5
	v_writelane_b32 v253, s41, 6
	v_writelane_b32 v253, s43, 7
	v_bfe_u32 v171, v0, 4, 2
	v_bfe_u32 v2, v0, 3, 25
	v_bfe_u32 v175, v0, 2, 4
	v_bfe_u32 v179, v0, 2, 2
	v_and_b32_e32 v182, 32, v0
	v_and_b32_e32 v172, 64, v0
	v_lshrrev_b32_e32 v180, 1, v0
	v_lshrrev_b32_e32 v181, 5, v0
	v_or_b32_e32 v178, 64, v2
	v_and_b32_e32 v170, 15, v0
	v_lshlrev_b32_e32 v173, 3, v171
	v_lshlrev_b32_e32 v174, 4, v171
	v_lshlrev_b32_e32 v176, 6, v0
	v_lshlrev_b32_e32 v177, 2, v0
	v_bitop3_b32 v159, v169, v182, 48 bitop3:0x6c
	v_or_b32_e32 v2, v159, v172
	v_and_b32_e32 v156, 24, v180
	v_and_b32_e32 v3, 4, v181
	v_and_or_b32 v4, v168, 48, v175
	v_lshrrev_b32_e32 v2, 1, v2
	v_or3_b32 v3, v3, v179, v156
	v_mul_u32_u24_e32 v160, 0xb00, v4
	v_and_or_b32 v5, v168, 32, v3
	v_or_b32_e32 v4, v2, v160
	s_add_u32 s3, s28, 0x2a00000
	v_lshlrev_b32_e32 v130, 1, v4
	v_mul_u32_u24_e32 v4, 0xb00, v5
	s_addc_u32 s35, s29, 0
	v_or_b32_e32 v4, v4, v2
	s_movk_i32 s0, 0x70
	s_add_u32 s8, s28, 0x9a00000
	v_lshlrev_b32_e32 v132, 1, v4
	v_and_or_b32 v4, v178, s0, v175
	s_movk_i32 s0, 0x60
	s_addc_u32 s9, s29, 0
	v_and_or_b32 v3, v178, s0, v3
	s_add_u32 s10, s28, 0x50000
	v_mul_u32_u24_e32 v161, 0xb00, v4
	v_mul_u32_u24_e32 v3, 0xb00, v3
	s_addc_u32 s11, s29, 0
	v_or_b32_e32 v4, v161, v2
	v_or_b32_e32 v2, v3, v2
	v_and_b32_e32 v158, 0x3c0, v176
	v_and_b32_e32 v157, 32, v177
	v_lshlrev_b32_e32 v134, 1, v4
	v_lshlrev_b32_e32 v136, 1, v2
	v_bitop3_b32 v162, v174, v157, v158 bitop3:0x36
	v_readfirstlane_b32 s6, v0
	s_nop 4
	s_branch .Lp7_r1

;     __device__ __forceinline__ void operator()(const pg8::f32x4 (&acc)[2][2][4][2], const pg8::Unit& u, int wr, int wc, int fr, int fq) const {
;         const int row0 = u.pm * 256 + wr * 64 + fr;
;         const int sect = u.pn >> 2;
; #pragma unroll
;         for (int ai = 0; ai < 2; ++ai)
; #pragma unroll
;             for (int m = 0; m < 4; ++m) {
;                 const int row = row0 + ai * 128 + m * 16; const float rs = rsqrtf(ss[row] * (1.f / DM) + EPS);
;                 if (u.pn < 12) {
;                     const float sc = (sect == 0) ? rs * QSCALE2 : rs;
.LBB0_1324:
	v_and_b32_e32 v209, 63, v0
	v_and_b32_e32 v210, 15, v209
	v_lshrrev_b32_e32 v211, 4, v209
	v_lshrrev_b32_e32 v212, 3, v209
	v_and_b32_e32 v213, 7, v209
	v_lshrrev_b32_e32 v209, 6, v0
	v_mul_u32_u24_e32 v209, 0x900, v209
	v_add_u32_e32 v209, 0x21000, v209
	v_mul_u32_u24_e32 v204, 0x90, v210
	v_lshl_add_u32 v204, v211, 5, v204
	v_add_u32_e32 v199, v209, v204
	v_mul_u32_u24_e32 v204, 0x90, v212
	v_lshl_add_u32 v204, v213, 4, v204
	v_add_u32_e32 v208, v209, v204
	v_sub_u32_e32 v204, v212, v210
	v_lshlrev_b32_e32 v204, 12, v204
	v_lshl_add_u32 v204, v213, 4, v204
	v_lshlrev_b32_e32 v209, 5, v211
	v_sub_u32_e32 v200, v204, v209
	v_ashrrev_i32_e32 v201, 31, v200
	v_add_u32_e32 v202, 0x8000, v200
	v_ashrrev_i32_e32 v203, 31, v202
	v_lshl_add_u32 v158, s4, 8, v145
	v_ashrrev_i32_e32 v159, 31, v158
	v_lshl_add_u64 v[160:161], v[158:159], 2, s[40:41]
	global_load_dword v191, v[160:161], off
	global_load_dword v192, v[160:161], off offset:64
	global_load_dword v193, v[160:161], off offset:128
	global_load_dword v194, v[160:161], off offset:192
	global_load_dword v195, v[160:161], off offset:512
	global_load_dword v196, v[160:161], off offset:576
	global_load_dword v197, v[160:161], off offset:640
	global_load_dword v198, v[160:161], off offset:704
	s_ashr_i32 s6, s8, 2
	s_cmp_gt_i32 s8, 11
	s_cselect_b64 s[80:81], -1, 0
	s_cmp_lt_u32 s8, 4
	s_cselect_b64 s[4:5], -1, 0
	s_cmp_eq_u32 s6, 1
	s_cselect_b64 s[10:11], -1, 0
	s_cmp_eq_u32 s6, 2
	s_cselect_b64 s[76:77], -1, 0
	s_cmp_gt_i32 s6, 0
	s_cselect_b64 s[74:75], -1, 0
	s_mov_b64 s[6:7], -1
	s_waitcnt vmcnt(0)
	v_mov_b32_e32 v130, v191
	v_fmamk_f32 v130, v130, 0x3a800000, v186
	v_cmp_gt_f32_e32 vcc, s94, v130
	v_mul_f32_e32 v131, 0x4b800000, v130
	s_nop 0
	v_cndmask_b32_e32 v130, v130, v131, vcc
	v_rsq_f32_e32 v130, v130
	s_nop 0
	v_mul_f32_e32 v131, 0x45800000, v130
	v_cndmask_b32_e32 v190, v130, v131, vcc
	s_and_b64 vcc, exec, s[80:81]
	s_cbranch_vccz .LBB0_1328
	s_and_saveexec_b64 s[78:79], s[48:49]
	s_cbranch_execz .LBB0_1327
; __device__ __forceinline__ float log_sigmoid(float z) { return fminf(z, 0.f) - __logf(1.f + __expf(-fabsf(z))); }
;     __device__ __forceinline__ void operator()(const pg8::f32x4 (&acc)[2][2][4][2], const pg8::Unit& u, int wr, int wc, int fr, int fq) const {
;     ...
;                 } else if (wc == 0 && fq < 2) {
;                     float* d = (row < MP) ? out + O_FLP + (size_t)row * 16 : out + O_FLS + (size_t)(row - MP) * 16;
; #pragma unroll
;                     for (int n = 0; n < 2; ++n) { const f32x4 v = acc[ai][0][m][n] * rs; f32x4 o;
; #pragma unroll
;                         for (int i = 0; i < 4; ++i) o[i] = log_sigmoid(v[i] + bf[8 * fq + 4 * n + i]);
;                         *(f32x4*)(d + 8 * fq + 4 * n) = o; }
	v_cmp_gt_i32_e32 vcc, s86, v158
	v_add_u32_e32 v130, 0xffffc000, v158
	v_readlane_b32 s52, v252, 0
	v_cndmask_b32_e32 v131, 0, v159, vcc
	v_cndmask_b32_e32 v130, v130, v158, vcc
	v_cndmask_b32_e32 v142, v187, v188, vcc
	v_readlane_b32 s58, v252, 6
	v_readlane_b32 s59, v252, 7
	v_lshlrev_b64 v[130:131], 6, v[130:131]
	v_readlane_b32 s53, v252, 1
	v_lshl_add_u64 v[132:133], s[58:59], 0, v[142:143]
	v_lshl_add_u64 v[130:131], v[132:133], 0, v[130:131]
	v_lshlrev_b32_e32 v142, 2, v144
	v_lshl_add_u64 v[162:163], v[130:131], 0, v[142:143]
	global_load_dwordx4 v[130:133], v[148:149], off
	v_readlane_b32 s54, v252, 2
	v_readlane_b32 s55, v252, 3
	v_readlane_b32 s56, v252, 4
	v_readlane_b32 s57, v252, 5
	s_waitcnt vmcnt(0)
	v_fma_f32 v142, v126, v190, v130
	v_min_f32_e32 v130, 0, v142
	v_mul_f32_e64 v142, |v142|, s95
	v_exp_f32_e32 v142, v142
	v_fma_f32 v132, v128, v190, v132
	v_min_f32_e32 v166, 0, v132
	v_mul_f32_e64 v132, |v132|, s95
	v_add_f32_e32 v142, 1.0, v142
	v_cmp_gt_f32_e32 vcc, s94, v142
	v_exp_f32_e32 v132, v132
	v_fmac_f32_e32 v133, v129, v190
	v_cndmask_b32_e64 v164, 0, 32, vcc
	v_ldexp_f32 v142, v142, v164
	v_log_f32_e32 v142, v142
	v_add_f32_e32 v132, 1.0, v132
	v_min_f32_e32 v167, 0, v133
	v_mul_f32_e64 v133, |v133|, s95
	v_mul_f32_e32 v164, 0x3f317217, v142
	v_fma_f32 v164, v142, s96, -v164
	v_fmac_f32_e32 v164, 0x3377d1cf, v142
	v_fmac_f32_e32 v164, 0x3f317217, v142
	v_cmp_lt_f32_e64 s[6:7], |v142|, s97
	v_exp_f32_e32 v133, v133
	s_nop 0
	v_cndmask_b32_e64 v142, v142, v164, s[6:7]
	v_cndmask_b32_e32 v164, 0, v189, vcc
	v_sub_f32_e32 v164, v142, v164
	v_fma_f32 v142, v127, v190, v131
	v_min_f32_e32 v131, 0, v142
	v_mul_f32_e64 v142, |v142|, s95
	v_exp_f32_e32 v142, v142
	v_add_f32_e32 v133, 1.0, v133
	v_add_f32_e32 v142, 1.0, v142
	v_cmp_gt_f32_e32 vcc, s94, v142
	s_nop 1
	v_cndmask_b32_e64 v165, 0, 32, vcc
	v_ldexp_f32 v142, v142, v165
	v_log_f32_e32 v142, v142
	s_nop 0
	v_mul_f32_e32 v165, 0x3f317217, v142
	v_fma_f32 v165, v142, s96, -v165
	v_fmac_f32_e32 v165, 0x3377d1cf, v142
	v_fmac_f32_e32 v165, 0x3f317217, v142
	v_cmp_lt_f32_e64 s[6:7], |v142|, s97
	s_nop 1
	v_cndmask_b32_e64 v142, v142, v165, s[6:7]
	v_cndmask_b32_e32 v165, 0, v189, vcc
	v_cmp_gt_f32_e32 vcc, s94, v132
	v_sub_f32_e32 v165, v142, v165
	v_pk_add_f32 v[130:131], v[130:131], v[164:165] neg_lo:[0,1] neg_hi:[0,1]
	v_cndmask_b32_e64 v142, 0, 32, vcc
	v_ldexp_f32 v132, v132, v142
	v_log_f32_e32 v132, v132
	s_nop 0
	v_mul_f32_e32 v142, 0x3f317217, v132
	v_fma_f32 v142, v132, s96, -v142
	v_fmac_f32_e32 v142, 0x3377d1cf, v132
	v_fmac_f32_e32 v142, 0x3f317217, v132
	v_cmp_lt_f32_e64 s[6:7], |v132|, s97
	s_nop 1
	v_cndmask_b32_e64 v132, v132, v142, s[6:7]
	v_cndmask_b32_e32 v142, 0, v189, vcc
	v_cmp_gt_f32_e32 vcc, s94, v133
	v_sub_f32_e32 v132, v132, v142
	s_nop 0
	v_cndmask_b32_e64 v142, 0, 32, vcc
	v_ldexp_f32 v133, v133, v142
	v_log_f32_e32 v133, v133
	s_nop 0
	v_mul_f32_e32 v142, 0x3f317217, v133
	v_fma_f32 v142, v133, s96, -v142
	v_fmac_f32_e32 v142, 0x3377d1cf, v133
	v_fmac_f32_e32 v142, 0x3f317217, v133
	v_cmp_lt_f32_e64 s[6:7], |v133|, s97
	s_nop 1
	v_cndmask_b32_e64 v133, v133, v142, s[6:7]
	v_cndmask_b32_e32 v142, 0, v189, vcc
	v_sub_f32_e32 v133, v133, v142
	v_pk_add_f32 v[132:133], v[166:167], v[132:133] neg_lo:[0,1] neg_hi:[0,1]
	global_store_dwordx4 v[162:163], v[130:133], off
	global_load_dwordx4 v[130:133], v[148:149], off offset:16
	s_waitcnt vmcnt(0)
	v_fma_f32 v142, v122, v190, v130
	v_min_f32_e32 v130, 0, v142
	v_mul_f32_e64 v142, |v142|, s95
	v_exp_f32_e32 v142, v142
	v_fma_f32 v132, v124, v190, v132
	v_min_f32_e32 v166, 0, v132
	v_mul_f32_e64 v132, |v132|, s95
	v_add_f32_e32 v142, 1.0, v142
	v_cmp_gt_f32_e32 vcc, s94, v142
	v_exp_f32_e32 v132, v132
	v_fmac_f32_e32 v133, v125, v190
	v_cndmask_b32_e64 v164, 0, 32, vcc
	v_ldexp_f32 v142, v142, v164
	v_log_f32_e32 v142, v142
	v_add_f32_e32 v132, 1.0, v132
	v_min_f32_e32 v167, 0, v133
	v_mul_f32_e64 v133, |v133|, s95
	v_mul_f32_e32 v164, 0x3f317217, v142
	v_fma_f32 v164, v142, s96, -v164
	v_fmac_f32_e32 v164, 0x3377d1cf, v142
	v_fmac_f32_e32 v164, 0x3f317217, v142
	v_cmp_lt_f32_e64 s[6:7], |v142|, s97
	v_exp_f32_e32 v133, v133
	s_nop 0
	v_cndmask_b32_e64 v142, v142, v164, s[6:7]
	v_cndmask_b32_e32 v164, 0, v189, vcc
	v_sub_f32_e32 v164, v142, v164
	v_fma_f32 v142, v123, v190, v131
	v_min_f32_e32 v131, 0, v142
	v_mul_f32_e64 v142, |v142|, s95
	v_exp_f32_e32 v142, v142
	v_add_f32_e32 v133, 1.0, v133
	v_add_f32_e32 v142, 1.0, v142
	v_cmp_gt_f32_e32 vcc, s94, v142
	s_nop 1
	v_cndmask_b32_e64 v165, 0, 32, vcc
	v_ldexp_f32 v142, v142, v165
	v_log_f32_e32 v142, v142
	s_nop 0
	v_mul_f32_e32 v165, 0x3f317217, v142
	v_fma_f32 v165, v142, s96, -v165
	v_fmac_f32_e32 v165, 0x3377d1cf, v142
	v_fmac_f32_e32 v165, 0x3f317217, v142
	v_cmp_lt_f32_e64 s[6:7], |v142|, s97
	s_nop 1
	v_cndmask_b32_e64 v142, v142, v165, s[6:7]
	v_cndmask_b32_e32 v165, 0, v189, vcc
	v_cmp_gt_f32_e32 vcc, s94, v132
	v_sub_f32_e32 v165, v142, v165
	v_pk_add_f32 v[130:131], v[130:131], v[164:165] neg_lo:[0,1] neg_hi:[0,1]
	v_cndmask_b32_e64 v142, 0, 32, vcc
	v_ldexp_f32 v132, v132, v142
	v_log_f32_e32 v132, v132
	s_nop 0
	v_mul_f32_e32 v142, 0x3f317217, v132
	v_fma_f32 v142, v132, s96, -v142
	v_fmac_f32_e32 v142, 0x3377d1cf, v132
	v_fmac_f32_e32 v142, 0x3f317217, v132
	v_cmp_lt_f32_e64 s[6:7], |v132|, s97
	s_nop 1
	v_cndmask_b32_e64 v132, v132, v142, s[6:7]
	v_cndmask_b32_e32 v142, 0, v189, vcc
	v_cmp_gt_f32_e32 vcc, s94, v133
	v_sub_f32_e32 v132, v132, v142
	s_nop 0
	v_cndmask_b32_e64 v142, 0, 32, vcc
	v_ldexp_f32 v133, v133, v142
	v_log_f32_e32 v133, v133
	s_nop 0
	v_mul_f32_e32 v142, 0x3f317217, v133
	v_fma_f32 v142, v133, s96, -v142
	v_fmac_f32_e32 v142, 0x3377d1cf, v133
	v_fmac_f32_e32 v142, 0x3f317217, v133
	v_cmp_lt_f32_e64 s[6:7], |v133|, s97
	s_nop 1
	v_cndmask_b32_e64 v133, v133, v142, s[6:7]
	v_cndmask_b32_e32 v142, 0, v189, vcc
	v_sub_f32_e32 v133, v133, v142
	v_pk_add_f32 v[132:133], v[166:167], v[132:133] neg_lo:[0,1] neg_hi:[0,1]
	global_store_dwordx4 v[162:163], v[130:133], off offset:16

; __device__ __forceinline__ unsigned pk(float lo, float hi) { return pg8::cvt_pk_bf16(lo, hi); }
;     __device__ __forceinline__ void operator()(const pg8::f32x4 (&acc)[2][2][4][2], const pg8::Unit& u, int wr, int wc, int fr, int fq) const {
;     ...
;                     for (int bj = 0; bj < 2; ++bj) { const f32x4 v0 = acc[ai][bj][m][0] * sc, v1 = acc[ai][bj][m][1] * sc;
;                         u32x4 w; w.x = pk(v0[0], v0[1]); w.y = pk(v0[2], v0[3]); w.z = pk(v1[0], v1[1]); w.w = pk(v1[2], v1[3]);
;                         const int cl = bj * 128 + wc * 32 + 8 * fq;
;                         *(u32x4*)(qkv + (size_t)row * NPJ + u.pn * 256 + cl) = w;
;                         if (sect > 0) { float* d = fdst + (u.pn & 3) * 256 + cl; __builtin_nontemporal_store(v0, (f32x4*)d); __builtin_nontemporal_store(v1, (f32x4*)(d + 4)); } }
.LBB0_1341:
	v_mul_f32_e32 v132, 0x3e38aa3b, v190
	v_mov_b64_e32 v[162:163], s[26:27]
	v_cndmask_b32_e64 v132, v190, v132, s[4:5]
	v_mad_i64_i32 v[162:163], s[8:9], v158, s63, v[162:163]
	s_lshl_b32 s24, s67, 2
	v_pk_mul_f32 v[128:129], v[128:129], v[132:133] op_sel_hi:[1,0]
	v_pk_mul_f32 v[126:127], v[126:127], v[132:133] op_sel_hi:[1,0]
	v_pk_mul_f32 v[124:125], v[124:125], v[132:133] op_sel_hi:[1,0]
	v_pk_mul_f32 v[122:123], v[122:123], v[132:133] op_sel_hi:[1,0]
	v_lshl_add_u64 v[162:163], s[78:79], 1, v[162:163]
	v_lshlrev_b32_e32 v142, 1, v146
	v_cndmask_b32_e64 v133, 0, 1, s[74:75]
	v_lshl_add_u64 v[130:131], v[130:131], 0, s[24:25]
	v_lshl_add_u64 v[162:163], v[162:163], 0, v[142:143]
	v_cmp_ne_u32_e64 s[8:9], 1, v133
	s_andn2_b64 vcc, exec, s[74:75]
	v_cvt_pk_bf16_f32 v164, v126, v127
	v_cvt_pk_bf16_f32 v165, v128, v129
	v_cvt_pk_bf16_f32 v166, v122, v123
	v_cvt_pk_bf16_f32 v167, v124, v125
	global_store_dwordx4 v[162:163], v[164:167], off
	s_cbranch_vccnz .LBB0_1343
	v_lshlrev_b32_e32 v142, 2, v146
	v_lshl_add_u64 v[164:165], v[130:131], 0, v[142:143]
	ds_write_b128 v199, v[126:129]
	ds_write_b128 v199, v[122:125] offset:16
	ds_read_b128 v[126:129], v208
	ds_read_b128 v[122:125], v208 offset:1152
	v_lshl_add_u64 v[204:205], v[164:165], 0, v[200:201]
	v_lshl_add_u64 v[206:207], v[164:165], 0, v[202:203]
	s_waitcnt lgkmcnt(0)
	global_store_dwordx4 v[204:205], v[126:129], off nt
	global_store_dwordx4 v[206:207], v[122:125], off nt
.LBB0_1343:
	v_mov_b32_e32 v133, v132
	s_nop 0
	v_mov_b32_e32 v122, v132
	v_mov_b32_e32 v123, v132
	v_pk_mul_f32 v[120:121], v[120:121], v[122:123]
	v_pk_mul_f32 v[118:119], v[118:119], v[132:133]
	v_pk_mul_f32 v[116:117], v[116:117], v[122:123]
	v_pk_mul_f32 v[114:115], v[114:115], v[132:133]
	s_and_b64 vcc, exec, s[8:9]
	v_cvt_pk_bf16_f32 v122, v118, v119
	v_cvt_pk_bf16_f32 v123, v120, v121
	v_cvt_pk_bf16_f32 v124, v114, v115
	v_cvt_pk_bf16_f32 v125, v116, v117
	global_store_dwordx4 v[162:163], v[122:125], off offset:256
	s_cbranch_vccnz .LBB0_1345
	v_lshlrev_b32_e32 v142, 2, v146
	v_lshl_add_u64 v[122:123], v[130:131], 0, v[142:143]
	ds_write_b128 v199, v[118:121]
	ds_write_b128 v199, v[114:117] offset:16
	ds_read_b128 v[118:121], v208
	ds_read_b128 v[114:117], v208 offset:1152
	v_lshl_add_u64 v[204:205], v[122:123], 0, v[200:201]
	v_lshl_add_u64 v[206:207], v[122:123], 0, v[202:203]
	s_waitcnt lgkmcnt(0)
	global_store_dwordx4 v[204:205], v[118:121], off offset:512 nt
	global_store_dwordx4 v[206:207], v[114:117], off offset:512 nt

; __device__ __forceinline__ unsigned pk(float lo, float hi) { return pg8::cvt_pk_bf16(lo, hi); }
;     __device__ __forceinline__ void operator()(const pg8::f32x4 (&acc)[2][2][4][2], const pg8::Unit& u, int wr, int wc, int fr, int fq) const {
;     ...
;                     for (int bj = 0; bj < 2; ++bj) { const f32x4 v0 = acc[ai][bj][m][0] * sc, v1 = acc[ai][bj][m][1] * sc;
;                         u32x4 w; w.x = pk(v0[0], v0[1]); w.y = pk(v0[2], v0[3]); w.z = pk(v1[0], v1[1]); w.w = pk(v1[2], v1[3]);
;                         const int cl = bj * 128 + wc * 32 + 8 * fq;
;                         *(u32x4*)(qkv + (size_t)row * NPJ + u.pn * 256 + cl) = w;
;                         if (sect > 0) { float* d = fdst + (u.pn & 3) * 256 + cl; __builtin_nontemporal_store(v0, (f32x4*)d); __builtin_nontemporal_store(v1, (f32x4*)(d + 4)); } }
.LBB0_1362:
	v_mul_f32_e32 v116, 0x3e38aa3b, v126
	v_mov_b64_e32 v[124:125], s[26:27]
	v_cndmask_b32_e64 v116, v126, v116, s[4:5]
	v_mad_i64_i32 v[118:119], s[10:11], v118, s63, v[124:125]
	s_lshl_b32 s24, s67, 2
	v_pk_mul_f32 v[112:113], v[112:113], v[116:117] op_sel_hi:[1,0]
	v_pk_mul_f32 v[110:111], v[110:111], v[116:117] op_sel_hi:[1,0]
	v_pk_mul_f32 v[108:109], v[108:109], v[116:117] op_sel_hi:[1,0]
	v_pk_mul_f32 v[106:107], v[106:107], v[116:117] op_sel_hi:[1,0]
	v_lshl_add_u64 v[118:119], s[78:79], 1, v[118:119]
	v_lshlrev_b32_e32 v142, 1, v146
	v_cndmask_b32_e64 v117, 0, 1, s[74:75]
	v_lshl_add_u64 v[114:115], v[114:115], 0, s[24:25]
	v_lshl_add_u64 v[118:119], v[118:119], 0, v[142:143]
	v_cmp_ne_u32_e64 s[10:11], 1, v117
	s_andn2_b64 vcc, exec, s[74:75]
	v_cvt_pk_bf16_f32 v120, v110, v111
	v_cvt_pk_bf16_f32 v121, v112, v113
	v_cvt_pk_bf16_f32 v122, v106, v107
	v_cvt_pk_bf16_f32 v123, v108, v109
	global_store_dwordx4 v[118:119], v[120:123], off
	s_cbranch_vccnz .LBB0_1364
	v_lshlrev_b32_e32 v142, 2, v146
	v_lshl_add_u64 v[120:121], v[114:115], 0, v[142:143]
	ds_write_b128 v199, v[110:113]
	ds_write_b128 v199, v[106:109] offset:16
	ds_read_b128 v[110:113], v208
	ds_read_b128 v[106:109], v208 offset:1152
	v_lshl_add_u64 v[204:205], v[120:121], 0, v[200:201]
	v_lshl_add_u64 v[206:207], v[120:121], 0, v[202:203]
	s_waitcnt lgkmcnt(0)
	global_store_dwordx4 v[204:205], v[110:113], off nt
	global_store_dwordx4 v[206:207], v[106:109], off nt
.LBB0_1364:
	v_mov_b32_e32 v117, v116
	s_nop 0
	v_mov_b32_e32 v106, v116
	v_mov_b32_e32 v107, v116
	v_pk_mul_f32 v[104:105], v[104:105], v[106:107]
	v_pk_mul_f32 v[102:103], v[102:103], v[116:117]
	v_pk_mul_f32 v[100:101], v[100:101], v[106:107]
	v_pk_mul_f32 v[98:99], v[98:99], v[116:117]
	s_and_b64 vcc, exec, s[10:11]
	v_cvt_pk_bf16_f32 v106, v102, v103
	v_cvt_pk_bf16_f32 v107, v104, v105
	v_cvt_pk_bf16_f32 v108, v98, v99
	v_cvt_pk_bf16_f32 v109, v100, v101
	global_store_dwordx4 v[118:119], v[106:109], off offset:256
	s_cbranch_vccnz .LBB0_1366
	v_lshlrev_b32_e32 v142, 2, v146
	v_lshl_add_u64 v[106:107], v[114:115], 0, v[142:143]
	ds_write_b128 v199, v[102:105]
	ds_write_b128 v199, v[98:101] offset:16
	ds_read_b128 v[102:105], v208
	ds_read_b128 v[98:101], v208 offset:1152
	v_lshl_add_u64 v[204:205], v[106:107], 0, v[200:201]
	v_lshl_add_u64 v[206:207], v[106:107], 0, v[202:203]
	s_waitcnt lgkmcnt(0)
	global_store_dwordx4 v[204:205], v[102:105], off offset:512 nt
	global_store_dwordx4 v[206:207], v[98:101], off offset:512 nt

; __device__ __forceinline__ unsigned pk(float lo, float hi) { return pg8::cvt_pk_bf16(lo, hi); }
;     __device__ __forceinline__ void operator()(const pg8::f32x4 (&acc)[2][2][4][2], const pg8::Unit& u, int wr, int wc, int fr, int fq) const {
;     ...
;                     for (int bj = 0; bj < 2; ++bj) { const f32x4 v0 = acc[ai][bj][m][0] * sc, v1 = acc[ai][bj][m][1] * sc;
;                         u32x4 w; w.x = pk(v0[0], v0[1]); w.y = pk(v0[2], v0[3]); w.z = pk(v1[0], v1[1]); w.w = pk(v1[2], v1[3]);
;                         const int cl = bj * 128 + wc * 32 + 8 * fq;
;                         *(u32x4*)(qkv + (size_t)row * NPJ + u.pn * 256 + cl) = w;
;                         if (sect > 0) { float* d = fdst + (u.pn & 3) * 256 + cl; __builtin_nontemporal_store(v0, (f32x4*)d); __builtin_nontemporal_store(v1, (f32x4*)(d + 4)); } }
.LBB0_1383:
	v_mul_f32_e32 v100, 0x3e38aa3b, v110
	v_mov_b64_e32 v[108:109], s[26:27]
	v_cndmask_b32_e64 v100, v110, v100, s[4:5]
	v_mad_i64_i32 v[102:103], s[10:11], v102, s63, v[108:109]
	s_lshl_b32 s24, s67, 2
	v_pk_mul_f32 v[96:97], v[96:97], v[100:101] op_sel_hi:[1,0]
	v_pk_mul_f32 v[94:95], v[94:95], v[100:101] op_sel_hi:[1,0]
	v_pk_mul_f32 v[92:93], v[92:93], v[100:101] op_sel_hi:[1,0]
	v_pk_mul_f32 v[90:91], v[90:91], v[100:101] op_sel_hi:[1,0]
	v_lshl_add_u64 v[102:103], s[78:79], 1, v[102:103]
	v_lshlrev_b32_e32 v142, 1, v146
	v_cndmask_b32_e64 v101, 0, 1, s[74:75]
	v_lshl_add_u64 v[98:99], v[98:99], 0, s[24:25]
	v_lshl_add_u64 v[102:103], v[102:103], 0, v[142:143]
	v_cmp_ne_u32_e64 s[10:11], 1, v101
	s_andn2_b64 vcc, exec, s[74:75]
	v_cvt_pk_bf16_f32 v104, v94, v95
	v_cvt_pk_bf16_f32 v105, v96, v97
	v_cvt_pk_bf16_f32 v106, v90, v91
	v_cvt_pk_bf16_f32 v107, v92, v93
	global_store_dwordx4 v[102:103], v[104:107], off
	s_cbranch_vccnz .LBB0_1385
	v_lshlrev_b32_e32 v142, 2, v146
	v_lshl_add_u64 v[104:105], v[98:99], 0, v[142:143]
	ds_write_b128 v199, v[94:97]
	ds_write_b128 v199, v[90:93] offset:16
	ds_read_b128 v[94:97], v208
	ds_read_b128 v[90:93], v208 offset:1152
	v_lshl_add_u64 v[204:205], v[104:105], 0, v[200:201]
	v_lshl_add_u64 v[206:207], v[104:105], 0, v[202:203]
	s_waitcnt lgkmcnt(0)
	global_store_dwordx4 v[204:205], v[94:97], off nt
	global_store_dwordx4 v[206:207], v[90:93], off nt
.LBB0_1385:
	v_mov_b32_e32 v101, v100
	s_nop 0
	v_mov_b32_e32 v90, v100
	v_mov_b32_e32 v91, v100
	v_pk_mul_f32 v[88:89], v[88:89], v[90:91]
	v_pk_mul_f32 v[86:87], v[86:87], v[100:101]
	v_pk_mul_f32 v[84:85], v[84:85], v[90:91]
	v_pk_mul_f32 v[82:83], v[82:83], v[100:101]
	s_and_b64 vcc, exec, s[10:11]
	v_cvt_pk_bf16_f32 v90, v86, v87
	v_cvt_pk_bf16_f32 v91, v88, v89
	v_cvt_pk_bf16_f32 v92, v82, v83
	v_cvt_pk_bf16_f32 v93, v84, v85
	global_store_dwordx4 v[102:103], v[90:93], off offset:256
	s_cbranch_vccnz .LBB0_1387
	v_lshlrev_b32_e32 v142, 2, v146
	v_lshl_add_u64 v[90:91], v[98:99], 0, v[142:143]
	ds_write_b128 v199, v[86:89]
	ds_write_b128 v199, v[82:85] offset:16
	ds_read_b128 v[86:89], v208
	ds_read_b128 v[82:85], v208 offset:1152
	v_lshl_add_u64 v[204:205], v[90:91], 0, v[200:201]
	v_lshl_add_u64 v[206:207], v[90:91], 0, v[202:203]
	s_waitcnt lgkmcnt(0)
	global_store_dwordx4 v[204:205], v[86:89], off offset:512 nt
	global_store_dwordx4 v[206:207], v[82:85], off offset:512 nt

; __device__ __forceinline__ unsigned pk(float lo, float hi) { return pg8::cvt_pk_bf16(lo, hi); }
;     __device__ __forceinline__ void operator()(const pg8::f32x4 (&acc)[2][2][4][2], const pg8::Unit& u, int wr, int wc, int fr, int fq) const {
;     ...
;                     for (int bj = 0; bj < 2; ++bj) { const f32x4 v0 = acc[ai][bj][m][0] * sc, v1 = acc[ai][bj][m][1] * sc;
;                         u32x4 w; w.x = pk(v0[0], v0[1]); w.y = pk(v0[2], v0[3]); w.z = pk(v1[0], v1[1]); w.w = pk(v1[2], v1[3]);
;                         const int cl = bj * 128 + wc * 32 + 8 * fq;
;                         *(u32x4*)(qkv + (size_t)row * NPJ + u.pn * 256 + cl) = w;
;                         if (sect > 0) { float* d = fdst + (u.pn & 3) * 256 + cl; __builtin_nontemporal_store(v0, (f32x4*)d); __builtin_nontemporal_store(v1, (f32x4*)(d + 4)); } }
.LBB0_1404:
	v_mul_f32_e32 v84, 0x3e38aa3b, v94
	v_mov_b64_e32 v[92:93], s[26:27]
	v_cndmask_b32_e64 v84, v94, v84, s[4:5]
	v_mad_i64_i32 v[86:87], s[10:11], v86, s63, v[92:93]
	s_lshl_b32 s24, s67, 2
	v_pk_mul_f32 v[80:81], v[80:81], v[84:85] op_sel_hi:[1,0]
	v_pk_mul_f32 v[78:79], v[78:79], v[84:85] op_sel_hi:[1,0]
	v_pk_mul_f32 v[76:77], v[76:77], v[84:85] op_sel_hi:[1,0]
	v_pk_mul_f32 v[74:75], v[74:75], v[84:85] op_sel_hi:[1,0]
	v_lshl_add_u64 v[86:87], s[78:79], 1, v[86:87]
	v_lshlrev_b32_e32 v142, 1, v146
	v_cndmask_b32_e64 v85, 0, 1, s[74:75]
	v_lshl_add_u64 v[82:83], v[82:83], 0, s[24:25]
	v_lshl_add_u64 v[86:87], v[86:87], 0, v[142:143]
	v_cmp_ne_u32_e64 s[10:11], 1, v85
	s_andn2_b64 vcc, exec, s[74:75]
	v_cvt_pk_bf16_f32 v88, v78, v79
	v_cvt_pk_bf16_f32 v89, v80, v81
	v_cvt_pk_bf16_f32 v90, v74, v75
	v_cvt_pk_bf16_f32 v91, v76, v77
	global_store_dwordx4 v[86:87], v[88:91], off
	s_cbranch_vccnz .LBB0_1406
	v_lshlrev_b32_e32 v142, 2, v146
	v_lshl_add_u64 v[88:89], v[82:83], 0, v[142:143]
	ds_write_b128 v199, v[78:81]
	ds_write_b128 v199, v[74:77] offset:16
	ds_read_b128 v[78:81], v208
	ds_read_b128 v[74:77], v208 offset:1152
	v_lshl_add_u64 v[204:205], v[88:89], 0, v[200:201]
	v_lshl_add_u64 v[206:207], v[88:89], 0, v[202:203]
	s_waitcnt lgkmcnt(0)
	global_store_dwordx4 v[204:205], v[78:81], off nt
	global_store_dwordx4 v[206:207], v[74:77], off nt
.LBB0_1406:
	v_mov_b32_e32 v85, v84
	s_nop 0
	v_mov_b32_e32 v74, v84
	v_mov_b32_e32 v75, v84
	v_pk_mul_f32 v[72:73], v[72:73], v[74:75]
	v_pk_mul_f32 v[70:71], v[70:71], v[84:85]
	v_pk_mul_f32 v[68:69], v[68:69], v[74:75]
	v_pk_mul_f32 v[66:67], v[66:67], v[84:85]
	s_and_b64 vcc, exec, s[10:11]
	v_cvt_pk_bf16_f32 v74, v70, v71
	v_cvt_pk_bf16_f32 v75, v72, v73
	v_cvt_pk_bf16_f32 v76, v66, v67
	v_cvt_pk_bf16_f32 v77, v68, v69
	global_store_dwordx4 v[86:87], v[74:77], off offset:256
	s_cbranch_vccnz .LBB0_1408
	v_lshlrev_b32_e32 v142, 2, v146
	v_lshl_add_u64 v[74:75], v[82:83], 0, v[142:143]
	ds_write_b128 v199, v[70:73]
	ds_write_b128 v199, v[66:69] offset:16
	ds_read_b128 v[70:73], v208
	ds_read_b128 v[66:69], v208 offset:1152
	v_lshl_add_u64 v[204:205], v[74:75], 0, v[200:201]
	v_lshl_add_u64 v[206:207], v[74:75], 0, v[202:203]
	s_waitcnt lgkmcnt(0)
	global_store_dwordx4 v[204:205], v[70:73], off offset:512 nt
	global_store_dwordx4 v[206:207], v[66:69], off offset:512 nt

; __device__ __forceinline__ unsigned pk(float lo, float hi) { return pg8::cvt_pk_bf16(lo, hi); }
;     __device__ __forceinline__ void operator()(const pg8::f32x4 (&acc)[2][2][4][2], const pg8::Unit& u, int wr, int wc, int fr, int fq) const {
;     ...
;                     for (int bj = 0; bj < 2; ++bj) { const f32x4 v0 = acc[ai][bj][m][0] * sc, v1 = acc[ai][bj][m][1] * sc;
;                         u32x4 w; w.x = pk(v0[0], v0[1]); w.y = pk(v0[2], v0[3]); w.z = pk(v1[0], v1[1]); w.w = pk(v1[2], v1[3]);
;                         const int cl = bj * 128 + wc * 32 + 8 * fq;
;                         *(u32x4*)(qkv + (size_t)row * NPJ + u.pn * 256 + cl) = w;
;                         if (sect > 0) { float* d = fdst + (u.pn & 3) * 256 + cl; __builtin_nontemporal_store(v0, (f32x4*)d); __builtin_nontemporal_store(v1, (f32x4*)(d + 4)); } }
.LBB0_1425:
	v_mul_f32_e32 v68, 0x3e38aa3b, v78
	v_mov_b64_e32 v[76:77], s[26:27]
	v_cndmask_b32_e64 v68, v78, v68, s[4:5]
	v_mad_i64_i32 v[70:71], s[10:11], v70, s63, v[76:77]
	s_lshl_b32 s24, s67, 2
	v_pk_mul_f32 v[64:65], v[64:65], v[68:69] op_sel_hi:[1,0]
	v_pk_mul_f32 v[62:63], v[62:63], v[68:69] op_sel_hi:[1,0]
	v_pk_mul_f32 v[60:61], v[60:61], v[68:69] op_sel_hi:[1,0]
	v_pk_mul_f32 v[58:59], v[58:59], v[68:69] op_sel_hi:[1,0]
	v_lshl_add_u64 v[70:71], s[78:79], 1, v[70:71]
	v_lshlrev_b32_e32 v142, 1, v146
	v_cndmask_b32_e64 v69, 0, 1, s[74:75]
	v_lshl_add_u64 v[66:67], v[66:67], 0, s[24:25]
	v_lshl_add_u64 v[70:71], v[70:71], 0, v[142:143]
	v_cmp_ne_u32_e64 s[10:11], 1, v69
	s_andn2_b64 vcc, exec, s[74:75]
	v_cvt_pk_bf16_f32 v72, v62, v63
	v_cvt_pk_bf16_f32 v73, v64, v65
	v_cvt_pk_bf16_f32 v74, v58, v59
	v_cvt_pk_bf16_f32 v75, v60, v61
	global_store_dwordx4 v[70:71], v[72:75], off
	s_cbranch_vccnz .LBB0_1427
	v_lshlrev_b32_e32 v142, 2, v146
	v_lshl_add_u64 v[72:73], v[66:67], 0, v[142:143]
	ds_write_b128 v199, v[62:65]
	ds_write_b128 v199, v[58:61] offset:16
	ds_read_b128 v[62:65], v208
	ds_read_b128 v[58:61], v208 offset:1152
	v_lshl_add_u64 v[204:205], v[72:73], 0, v[200:201]
	v_lshl_add_u64 v[206:207], v[72:73], 0, v[202:203]
	s_waitcnt lgkmcnt(0)
	global_store_dwordx4 v[204:205], v[62:65], off nt
	global_store_dwordx4 v[206:207], v[58:61], off nt
.LBB0_1427:
	v_mov_b32_e32 v69, v68
	s_nop 0
	v_mov_b32_e32 v58, v68
	v_mov_b32_e32 v59, v68
	v_pk_mul_f32 v[56:57], v[56:57], v[58:59]
	v_pk_mul_f32 v[54:55], v[54:55], v[68:69]
	v_pk_mul_f32 v[52:53], v[52:53], v[58:59]
	v_pk_mul_f32 v[50:51], v[50:51], v[68:69]
	s_and_b64 vcc, exec, s[10:11]
	v_cvt_pk_bf16_f32 v58, v54, v55
	v_cvt_pk_bf16_f32 v59, v56, v57
	v_cvt_pk_bf16_f32 v60, v50, v51
	v_cvt_pk_bf16_f32 v61, v52, v53
	global_store_dwordx4 v[70:71], v[58:61], off offset:256
	s_cbranch_vccnz .LBB0_1429
	v_lshlrev_b32_e32 v142, 2, v146
	v_lshl_add_u64 v[58:59], v[66:67], 0, v[142:143]
	ds_write_b128 v199, v[54:57]
	ds_write_b128 v199, v[50:53] offset:16
	ds_read_b128 v[54:57], v208
	ds_read_b128 v[50:53], v208 offset:1152
	v_lshl_add_u64 v[204:205], v[58:59], 0, v[200:201]
	v_lshl_add_u64 v[206:207], v[58:59], 0, v[202:203]
	s_waitcnt lgkmcnt(0)
	global_store_dwordx4 v[204:205], v[54:57], off offset:512 nt
	global_store_dwordx4 v[206:207], v[50:53], off offset:512 nt

; __device__ __forceinline__ unsigned pk(float lo, float hi) { return pg8::cvt_pk_bf16(lo, hi); }
;     __device__ __forceinline__ void operator()(const pg8::f32x4 (&acc)[2][2][4][2], const pg8::Unit& u, int wr, int wc, int fr, int fq) const {
;     ...
;                     for (int bj = 0; bj < 2; ++bj) { const f32x4 v0 = acc[ai][bj][m][0] * sc, v1 = acc[ai][bj][m][1] * sc;
;                         u32x4 w; w.x = pk(v0[0], v0[1]); w.y = pk(v0[2], v0[3]); w.z = pk(v1[0], v1[1]); w.w = pk(v1[2], v1[3]);
;                         const int cl = bj * 128 + wc * 32 + 8 * fq;
;                         *(u32x4*)(qkv + (size_t)row * NPJ + u.pn * 256 + cl) = w;
;                         if (sect > 0) { float* d = fdst + (u.pn & 3) * 256 + cl; __builtin_nontemporal_store(v0, (f32x4*)d); __builtin_nontemporal_store(v1, (f32x4*)(d + 4)); } }
.LBB0_1446:
	v_mul_f32_e32 v52, 0x3e38aa3b, v62
	v_mov_b64_e32 v[60:61], s[26:27]
	v_cndmask_b32_e64 v52, v62, v52, s[4:5]
	v_mad_i64_i32 v[54:55], s[10:11], v54, s63, v[60:61]
	s_lshl_b32 s24, s67, 2
	v_pk_mul_f32 v[48:49], v[48:49], v[52:53] op_sel_hi:[1,0]
	v_pk_mul_f32 v[46:47], v[46:47], v[52:53] op_sel_hi:[1,0]
	v_pk_mul_f32 v[44:45], v[44:45], v[52:53] op_sel_hi:[1,0]
	v_pk_mul_f32 v[42:43], v[42:43], v[52:53] op_sel_hi:[1,0]
	v_lshl_add_u64 v[54:55], s[78:79], 1, v[54:55]
	v_lshlrev_b32_e32 v142, 1, v146
	v_cndmask_b32_e64 v53, 0, 1, s[74:75]
	v_lshl_add_u64 v[50:51], v[50:51], 0, s[24:25]
	v_lshl_add_u64 v[54:55], v[54:55], 0, v[142:143]
	v_cmp_ne_u32_e64 s[10:11], 1, v53
	s_andn2_b64 vcc, exec, s[74:75]
	v_cvt_pk_bf16_f32 v56, v46, v47
	v_cvt_pk_bf16_f32 v57, v48, v49
	v_cvt_pk_bf16_f32 v58, v42, v43
	v_cvt_pk_bf16_f32 v59, v44, v45
	global_store_dwordx4 v[54:55], v[56:59], off
	s_cbranch_vccnz .LBB0_1448
	v_lshlrev_b32_e32 v142, 2, v146
	v_lshl_add_u64 v[56:57], v[50:51], 0, v[142:143]
	ds_write_b128 v199, v[46:49]
	ds_write_b128 v199, v[42:45] offset:16
	ds_read_b128 v[46:49], v208
	ds_read_b128 v[42:45], v208 offset:1152
	v_lshl_add_u64 v[204:205], v[56:57], 0, v[200:201]
	v_lshl_add_u64 v[206:207], v[56:57], 0, v[202:203]
	s_waitcnt lgkmcnt(0)
	global_store_dwordx4 v[204:205], v[46:49], off nt
	global_store_dwordx4 v[206:207], v[42:45], off nt
.LBB0_1448:
	v_mov_b32_e32 v53, v52
	s_nop 0
	v_mov_b32_e32 v42, v52
	v_mov_b32_e32 v43, v52
	v_pk_mul_f32 v[40:41], v[40:41], v[42:43]
	v_pk_mul_f32 v[38:39], v[38:39], v[52:53]
	v_pk_mul_f32 v[36:37], v[36:37], v[42:43]
	v_pk_mul_f32 v[34:35], v[34:35], v[52:53]
	s_and_b64 vcc, exec, s[10:11]
	v_cvt_pk_bf16_f32 v42, v38, v39
	v_cvt_pk_bf16_f32 v43, v40, v41
	v_cvt_pk_bf16_f32 v44, v34, v35
	v_cvt_pk_bf16_f32 v45, v36, v37
	global_store_dwordx4 v[54:55], v[42:45], off offset:256
	s_cbranch_vccnz .LBB0_1450
	v_lshlrev_b32_e32 v142, 2, v146
	v_lshl_add_u64 v[42:43], v[50:51], 0, v[142:143]
	ds_write_b128 v199, v[38:41]
	ds_write_b128 v199, v[34:37] offset:16
	ds_read_b128 v[38:41], v208
	ds_read_b128 v[34:37], v208 offset:1152
	v_lshl_add_u64 v[204:205], v[42:43], 0, v[200:201]
	v_lshl_add_u64 v[206:207], v[42:43], 0, v[202:203]
	s_waitcnt lgkmcnt(0)
	global_store_dwordx4 v[204:205], v[38:41], off offset:512 nt
	global_store_dwordx4 v[206:207], v[34:37], off offset:512 nt

; __device__ __forceinline__ unsigned pk(float lo, float hi) { return pg8::cvt_pk_bf16(lo, hi); }
;     __device__ __forceinline__ void operator()(const pg8::f32x4 (&acc)[2][2][4][2], const pg8::Unit& u, int wr, int wc, int fr, int fq) const {
;     ...
;                     for (int bj = 0; bj < 2; ++bj) { const f32x4 v0 = acc[ai][bj][m][0] * sc, v1 = acc[ai][bj][m][1] * sc;
;                         u32x4 w; w.x = pk(v0[0], v0[1]); w.y = pk(v0[2], v0[3]); w.z = pk(v1[0], v1[1]); w.w = pk(v1[2], v1[3]);
;                         const int cl = bj * 128 + wc * 32 + 8 * fq;
;                         *(u32x4*)(qkv + (size_t)row * NPJ + u.pn * 256 + cl) = w;
;                         if (sect > 0) { float* d = fdst + (u.pn & 3) * 256 + cl; __builtin_nontemporal_store(v0, (f32x4*)d); __builtin_nontemporal_store(v1, (f32x4*)(d + 4)); } }
.LBB0_1467:
	v_mul_f32_e32 v36, 0x3e38aa3b, v46
	v_mov_b64_e32 v[44:45], s[26:27]
	v_cndmask_b32_e64 v36, v46, v36, s[4:5]
	v_mad_i64_i32 v[38:39], s[10:11], v38, s63, v[44:45]
	s_lshl_b32 s24, s67, 2
	v_pk_mul_f32 v[32:33], v[32:33], v[36:37] op_sel_hi:[1,0]
	v_pk_mul_f32 v[30:31], v[30:31], v[36:37] op_sel_hi:[1,0]
	v_pk_mul_f32 v[28:29], v[28:29], v[36:37] op_sel_hi:[1,0]
	v_pk_mul_f32 v[26:27], v[26:27], v[36:37] op_sel_hi:[1,0]
	v_lshl_add_u64 v[38:39], s[78:79], 1, v[38:39]
	v_lshlrev_b32_e32 v142, 1, v146
	v_cndmask_b32_e64 v37, 0, 1, s[74:75]
	v_lshl_add_u64 v[34:35], v[34:35], 0, s[24:25]
	v_lshl_add_u64 v[38:39], v[38:39], 0, v[142:143]
	v_cmp_ne_u32_e64 s[10:11], 1, v37
	s_andn2_b64 vcc, exec, s[74:75]
	v_cvt_pk_bf16_f32 v40, v30, v31
	v_cvt_pk_bf16_f32 v41, v32, v33
	v_cvt_pk_bf16_f32 v42, v26, v27
	v_cvt_pk_bf16_f32 v43, v28, v29
	global_store_dwordx4 v[38:39], v[40:43], off
	s_cbranch_vccnz .LBB0_1469
	v_lshlrev_b32_e32 v142, 2, v146
	v_lshl_add_u64 v[40:41], v[34:35], 0, v[142:143]
	ds_write_b128 v199, v[30:33]
	ds_write_b128 v199, v[26:29] offset:16
	ds_read_b128 v[30:33], v208
	ds_read_b128 v[26:29], v208 offset:1152
	v_lshl_add_u64 v[204:205], v[40:41], 0, v[200:201]
	v_lshl_add_u64 v[206:207], v[40:41], 0, v[202:203]
	s_waitcnt lgkmcnt(0)
	global_store_dwordx4 v[204:205], v[30:33], off nt
	global_store_dwordx4 v[206:207], v[26:29], off nt
.LBB0_1469:
	v_mov_b32_e32 v37, v36
	s_nop 0
	v_mov_b32_e32 v26, v36
	v_mov_b32_e32 v27, v36
	v_pk_mul_f32 v[24:25], v[24:25], v[26:27]
	v_pk_mul_f32 v[22:23], v[22:23], v[36:37]
	v_pk_mul_f32 v[20:21], v[20:21], v[26:27]
	v_pk_mul_f32 v[18:19], v[18:19], v[36:37]
	s_and_b64 vcc, exec, s[10:11]
	v_cvt_pk_bf16_f32 v26, v22, v23
	v_cvt_pk_bf16_f32 v27, v24, v25
	v_cvt_pk_bf16_f32 v28, v18, v19
	v_cvt_pk_bf16_f32 v29, v20, v21
	global_store_dwordx4 v[38:39], v[26:29], off offset:256
	s_cbranch_vccnz .LBB0_1471
	v_lshlrev_b32_e32 v142, 2, v146
	v_lshl_add_u64 v[26:27], v[34:35], 0, v[142:143]
	ds_write_b128 v199, v[22:25]
	ds_write_b128 v199, v[18:21] offset:16
	ds_read_b128 v[22:25], v208
	ds_read_b128 v[18:21], v208 offset:1152
	v_lshl_add_u64 v[204:205], v[26:27], 0, v[200:201]
	v_lshl_add_u64 v[206:207], v[26:27], 0, v[202:203]
	s_waitcnt lgkmcnt(0)
	global_store_dwordx4 v[204:205], v[22:25], off offset:512 nt
	global_store_dwordx4 v[206:207], v[18:21], off offset:512 nt

; __device__ __forceinline__ unsigned pk(float lo, float hi) { return pg8::cvt_pk_bf16(lo, hi); }
;     __device__ __forceinline__ void operator()(const pg8::f32x4 (&acc)[2][2][4][2], const pg8::Unit& u, int wr, int wc, int fr, int fq) const {
;     ...
;                     for (int bj = 0; bj < 2; ++bj) { const f32x4 v0 = acc[ai][bj][m][0] * sc, v1 = acc[ai][bj][m][1] * sc;
;                         u32x4 w; w.x = pk(v0[0], v0[1]); w.y = pk(v0[2], v0[3]); w.z = pk(v1[0], v1[1]); w.w = pk(v1[2], v1[3]);
;                         const int cl = bj * 128 + wc * 32 + 8 * fq;
;                         *(u32x4*)(qkv + (size_t)row * NPJ + u.pn * 256 + cl) = w;
;                         if (sect > 0) { float* d = fdst + (u.pn & 3) * 256 + cl; __builtin_nontemporal_store(v0, (f32x4*)d); __builtin_nontemporal_store(v1, (f32x4*)(d + 4)); } }
.LBB0_1488:
	v_mul_f32_e32 v20, 0x3e38aa3b, v30
	v_mov_b64_e32 v[28:29], s[26:27]
	v_cndmask_b32_e64 v20, v30, v20, s[4:5]
	v_mad_i64_i32 v[22:23], s[4:5], v22, s63, v[28:29]
	s_lshl_b32 s24, s67, 2
	v_pk_mul_f32 v[16:17], v[16:17], v[20:21] op_sel_hi:[1,0]
	v_pk_mul_f32 v[14:15], v[14:15], v[20:21] op_sel_hi:[1,0]
	v_pk_mul_f32 v[12:13], v[12:13], v[20:21] op_sel_hi:[1,0]
	v_pk_mul_f32 v[10:11], v[10:11], v[20:21] op_sel_hi:[1,0]
	v_lshl_add_u64 v[22:23], s[78:79], 1, v[22:23]
	v_lshlrev_b32_e32 v142, 1, v146
	v_cndmask_b32_e64 v21, 0, 1, s[74:75]
	v_lshl_add_u64 v[18:19], v[18:19], 0, s[24:25]
	v_lshl_add_u64 v[22:23], v[22:23], 0, v[142:143]
	v_cmp_ne_u32_e64 s[4:5], 1, v21
	s_andn2_b64 vcc, exec, s[74:75]
	v_lshlrev_b32_e32 v142, 2, v146
	v_cvt_pk_bf16_f32 v24, v14, v15
	v_cvt_pk_bf16_f32 v25, v16, v17
	v_cvt_pk_bf16_f32 v26, v10, v11
	v_cvt_pk_bf16_f32 v27, v12, v13
	global_store_dwordx4 v[22:23], v[24:27], off
	s_cbranch_vccnz .LBB0_1490
	s_nop 0
	v_lshl_add_u64 v[24:25], v[18:19], 0, v[142:143]
	ds_write_b128 v199, v[14:17]
	ds_write_b128 v199, v[10:13] offset:16
	ds_read_b128 v[14:17], v208
	ds_read_b128 v[10:13], v208 offset:1152
	v_lshl_add_u64 v[204:205], v[24:25], 0, v[200:201]
	v_lshl_add_u64 v[206:207], v[24:25], 0, v[202:203]
	s_waitcnt lgkmcnt(0)
	global_store_dwordx4 v[204:205], v[14:17], off nt
	global_store_dwordx4 v[206:207], v[10:13], off nt
.LBB0_1490:
	v_mov_b32_e32 v21, v20
	s_nop 0
	v_mov_b32_e32 v10, v20
	v_mov_b32_e32 v11, v20
	v_pk_mul_f32 v[8:9], v[8:9], v[10:11]
	v_pk_mul_f32 v[6:7], v[6:7], v[20:21]
	v_pk_mul_f32 v[4:5], v[4:5], v[10:11]
	v_pk_mul_f32 v[2:3], v[2:3], v[20:21]
	s_and_b64 vcc, exec, s[4:5]
	v_cvt_pk_bf16_f32 v10, v6, v7
	v_cvt_pk_bf16_f32 v11, v8, v9
	v_cvt_pk_bf16_f32 v12, v2, v3
	v_cvt_pk_bf16_f32 v13, v4, v5
	global_store_dwordx4 v[22:23], v[10:13], off offset:256
	s_cbranch_vccnz .LBB0_1492
	s_nop 0
	v_lshl_add_u64 v[10:11], v[18:19], 0, v[142:143]
	ds_write_b128 v199, v[6:9]
	ds_write_b128 v199, v[2:5] offset:16
	ds_read_b128 v[6:9], v208
	ds_read_b128 v[2:5], v208 offset:1152
	v_lshl_add_u64 v[204:205], v[10:11], 0, v[200:201]
	v_lshl_add_u64 v[206:207], v[10:11], 0, v[202:203]
	s_waitcnt lgkmcnt(0)
	global_store_dwordx4 v[204:205], v[6:9], off offset:512 nt
	global_store_dwordx4 v[206:207], v[2:5], off offset:512 nt

;     __device__ __forceinline__ void operator()(const pg8::f32x4 (&acc)[2][2][4][2], const pg8::Unit& u, int wr, int wc, int fr, int fq) const {
; #pragma unroll
;         for (int ai = 0; ai < 2; ++ai)
; #pragma unroll
;             for (int m = 0; m < 4; ++m) { float* rowp = part + (size_t)(ai * 128 + wr * 64 + m * 16 + fr) * 256 + wc * 32 + 8 * fq;
; #pragma unroll
;                 for (int bj = 0; bj < 2; ++bj) { *(f32x4*)(rowp + bj * 128) = acc[ai][bj][m][0]; *(f32x4*)(rowp + bj * 128 + 4) = acc[ai][bj][m][1]; } }
.LBB0_2149:
	s_add_u32 s0, s28, 0x25e00000
	s_addc_u32 s1, s29, 0
	s_ashr_i32 s3, s2, 31
	s_lshl_b64 s[4:5], s[2:3], 18
	v_mov_b32_e32 v131, 0
	s_add_u32 s4, s0, s4
	v_add_u32_e32 v130, 0xb0, v138
	v_add_u32_e32 v134, 0xa0, v138
	v_mov_b32_e32 v135, v131
	v_add_u32_e32 v136, 0x90, v138
	v_mov_b32_e32 v137, v131
	v_add_u32_e32 v140, 0x80, v138
	v_mov_b32_e32 v141, v131
	v_or_b32_e32 v142, 48, v138
	v_mov_b32_e32 v143, v131
	v_or_b32_e32 v144, 32, v138
	v_mov_b32_e32 v145, v131
	v_or_b32_e32 v146, 16, v138
	v_mov_b32_e32 v147, v131
	v_mov_b32_e32 v139, v131
	s_addc_u32 s5, s1, s5
	v_lshlrev_b64 v[132:133], 10, v[130:131]
	v_lshlrev_b64 v[134:135], 10, v[134:135]
	v_lshlrev_b64 v[136:137], 10, v[136:137]
	v_lshlrev_b64 v[140:141], 10, v[140:141]
	v_lshlrev_b64 v[142:143], 10, v[142:143]
	v_lshlrev_b64 v[144:145], 10, v[144:145]
	v_lshlrev_b64 v[146:147], 10, v[146:147]
	v_lshlrev_b64 v[138:139], 10, v[138:139]
	s_mov_b32 s7, 0
	v_lshl_add_u64 v[132:133], s[4:5], 0, v[132:133]
	s_lshl_b32 s6, s20, 2
	v_lshl_add_u64 v[134:135], s[4:5], 0, v[134:135]
	v_lshl_add_u64 v[136:137], s[4:5], 0, v[136:137]
	v_lshl_add_u64 v[140:141], s[4:5], 0, v[140:141]
	v_lshl_add_u64 v[142:143], s[4:5], 0, v[142:143]
	v_lshl_add_u64 v[144:145], s[4:5], 0, v[144:145]
	v_lshl_add_u64 v[146:147], s[4:5], 0, v[146:147]
	v_lshl_add_u64 v[138:139], s[4:5], 0, v[138:139]
	v_lshl_add_u64 v[132:133], v[132:133], 0, s[6:7]
	v_lshlrev_b32_e32 v130, 2, v156
	v_lshl_add_u64 v[134:135], v[134:135], 0, s[6:7]
	v_lshl_add_u64 v[136:137], v[136:137], 0, s[6:7]
	v_lshl_add_u64 v[140:141], v[140:141], 0, s[6:7]
	v_lshl_add_u64 v[142:143], v[142:143], 0, s[6:7]
	v_lshl_add_u64 v[144:145], v[144:145], 0, s[6:7]
	v_lshl_add_u64 v[146:147], v[146:147], 0, s[6:7]
	v_lshl_add_u64 v[138:139], v[138:139], 0, s[6:7]
	v_lshl_add_u64 v[132:133], v[132:133], 0, v[130:131]
	v_lshl_add_u64 v[134:135], v[134:135], 0, v[130:131]
	v_lshl_add_u64 v[136:137], v[136:137], 0, v[130:131]
	v_lshl_add_u64 v[140:141], v[140:141], 0, v[130:131]
	v_lshl_add_u64 v[142:143], v[142:143], 0, v[130:131]
	v_lshl_add_u64 v[144:145], v[144:145], 0, v[130:131]
	v_lshl_add_u64 v[146:147], v[146:147], 0, v[130:131]
	v_lshl_add_u64 v[130:131], v[138:139], 0, v[130:131]
	v_and_b32_e32 v246, 63, v0
	v_and_b32_e32 v158, 15, v246
	v_lshrrev_b32_e32 v159, 4, v246
	v_lshrrev_b32_e32 v160, 3, v246
	v_and_b32_e32 v161, 7, v246
	v_lshrrev_b32_e32 v246, 6, v0
	v_mul_u32_u24_e32 v246, 0x900, v246
	v_add_u32_e32 v246, 0x21000, v246
	v_mul_u32_u24_e32 v150, 0x90, v158
	v_lshl_add_u32 v150, v159, 5, v150
	v_add_u32_e32 v242, v246, v150
	v_mul_u32_u24_e32 v150, 0x90, v160
	v_lshl_add_u32 v150, v161, 4, v150
	v_add_u32_e32 v245, v246, v150
	v_sub_u32_e32 v150, v160, v158
	v_lshlrev_b32_e32 v150, 10, v150
	v_lshl_add_u32 v150, v161, 4, v150
	v_lshlrev_b32_e32 v246, 5, v159
	v_sub_u32_e32 v138, v150, v246
	v_ashrrev_i32_e32 v139, 31, v138
	v_add_u32_e32 v148, 0x2000, v138
	v_ashrrev_i32_e32 v149, 31, v148
	ds_write_b128 v242, v[126:129]
	ds_write_b128 v242, v[122:125] offset:16
	ds_read_b128 v[126:129], v245
	ds_read_b128 v[122:125], v245 offset:1152
	ds_write_b128 v242, v[102:105]
	ds_write_b128 v242, v[94:97] offset:16
	ds_read_b128 v[102:105], v245
	ds_read_b128 v[94:97], v245 offset:1152
	s_waitcnt lgkmcnt(4)
	v_lshl_add_u64 v[150:151], v[130:131], 0, v[138:139]
	v_lshl_add_u64 v[152:153], v[130:131], 0, v[148:149]
	global_store_dwordx4 v[150:151], v[126:129], off
	global_store_dwordx4 v[152:153], v[122:125], off
	ds_write_b128 v242, v[118:121]
	ds_write_b128 v242, v[114:117] offset:16
	ds_read_b128 v[118:121], v245
	ds_read_b128 v[114:117], v245 offset:1152
	s_waitcnt lgkmcnt(4)
	v_lshl_add_u64 v[154:155], v[130:131], 0, v[138:139]
	v_lshl_add_u64 v[156:157], v[130:131], 0, v[148:149]
	global_store_dwordx4 v[154:155], v[102:105], off offset:512
	global_store_dwordx4 v[156:157], v[94:97], off offset:512
	ds_write_b128 v242, v[86:89]
	ds_write_b128 v242, v[82:85] offset:16
	ds_read_b128 v[86:89], v245
	ds_read_b128 v[82:85], v245 offset:1152
	s_waitcnt lgkmcnt(4)
	v_lshl_add_u64 v[150:151], v[146:147], 0, v[138:139]
	v_lshl_add_u64 v[152:153], v[146:147], 0, v[148:149]
	global_store_dwordx4 v[150:151], v[118:121], off
	global_store_dwordx4 v[152:153], v[114:117], off
	ds_write_b128 v242, v[110:113]
	ds_write_b128 v242, v[106:109] offset:16
	ds_read_b128 v[110:113], v245
	ds_read_b128 v[106:109], v245 offset:1152
	s_waitcnt lgkmcnt(4)
	v_lshl_add_u64 v[154:155], v[146:147], 0, v[138:139]
	v_lshl_add_u64 v[156:157], v[146:147], 0, v[148:149]
	global_store_dwordx4 v[154:155], v[86:89], off offset:512
	global_store_dwordx4 v[156:157], v[82:85], off offset:512
	ds_write_b128 v242, v[78:81]
	ds_write_b128 v242, v[74:77] offset:16
	ds_read_b128 v[78:81], v245
	ds_read_b128 v[74:77], v245 offset:1152
	s_waitcnt lgkmcnt(4)
	v_lshl_add_u64 v[150:151], v[144:145], 0, v[138:139]
	v_lshl_add_u64 v[152:153], v[144:145], 0, v[148:149]
	global_store_dwordx4 v[150:151], v[110:113], off
	global_store_dwordx4 v[152:153], v[106:109], off
	ds_write_b128 v242, v[98:101]
	ds_write_b128 v242, v[90:93] offset:16
	ds_read_b128 v[98:101], v245
	ds_read_b128 v[90:93], v245 offset:1152
	s_waitcnt lgkmcnt(4)
	v_lshl_add_u64 v[154:155], v[144:145], 0, v[138:139]
	v_lshl_add_u64 v[156:157], v[144:145], 0, v[148:149]
	global_store_dwordx4 v[154:155], v[78:81], off offset:512
	global_store_dwordx4 v[156:157], v[74:77], off offset:512
	ds_write_b128 v242, v[70:73]
	ds_write_b128 v242, v[66:69] offset:16
	ds_read_b128 v[70:73], v245
	ds_read_b128 v[66:69], v245 offset:1152
	s_waitcnt lgkmcnt(4)
; #define PG8_WAIT_V(n) asm volatile("s_waitcnt vmcnt(" #n ")" ::: "memory")
; #define PG8_BAR __builtin_amdgcn_s_barrier()
; template <class Epi, class Sched, bool ALIGN_EPI = false, bool SP2 = false>
; __device__ __forceinline__ void gemm_phase(PG8_LAS unsigned char* lds, const Gemm g, const Sched& S, const Epi& E) {
;     ...
;     PG8_WAIT_V(0);
;     if constexpr (!ALIGN_EPI) { if (wr == 0) PG8_BAR; }
;     PG8_BAR;
;     __device__ __forceinline__ void operator()(const pg8::f32x4 (&acc)[2][2][4][2], const pg8::Unit& u, int wr, int wc, int fr, int fq) const {
; #pragma unroll
;         for (int ai = 0; ai < 2; ++ai)
; #pragma unroll
;             for (int m = 0; m < 4; ++m) { float* rowp = part + (size_t)(ai * 128 + wr * 64 + m * 16 + fr) * 256 + wc * 32 + 8 * fq;
; #pragma unroll
;                 for (int bj = 0; bj < 2; ++bj) { *(f32x4*)(rowp + bj * 128) = acc[ai][bj][m][0]; *(f32x4*)(rowp + bj * 128 + 4) = acc[ai][bj][m][1]; } }
	v_lshl_add_u64 v[150:151], v[142:143], 0, v[138:139]
	v_lshl_add_u64 v[152:153], v[142:143], 0, v[148:149]
	global_store_dwordx4 v[150:151], v[98:101], off
	global_store_dwordx4 v[152:153], v[90:93], off
	ds_write_b128 v242, v[62:65]
	ds_write_b128 v242, v[58:61] offset:16
	ds_read_b128 v[62:65], v245
	ds_read_b128 v[58:61], v245 offset:1152
	s_waitcnt lgkmcnt(4)
	v_lshl_add_u64 v[154:155], v[142:143], 0, v[138:139]
	v_lshl_add_u64 v[156:157], v[142:143], 0, v[148:149]
	global_store_dwordx4 v[154:155], v[70:73], off offset:512
	global_store_dwordx4 v[156:157], v[66:69], off offset:512
	ds_write_b128 v242, v[38:41]
	ds_write_b128 v242, v[30:33] offset:16
	ds_read_b128 v[38:41], v245
	ds_read_b128 v[30:33], v245 offset:1152
	s_waitcnt lgkmcnt(4)
	v_lshl_add_u64 v[150:151], v[140:141], 0, v[138:139]
	v_lshl_add_u64 v[152:153], v[140:141], 0, v[148:149]
	global_store_dwordx4 v[150:151], v[62:65], off
	global_store_dwordx4 v[152:153], v[58:61], off
	ds_write_b128 v242, v[54:57]
	ds_write_b128 v242, v[50:53] offset:16
	ds_read_b128 v[54:57], v245
	ds_read_b128 v[50:53], v245 offset:1152
	s_waitcnt lgkmcnt(4)
	v_lshl_add_u64 v[154:155], v[140:141], 0, v[138:139]
	v_lshl_add_u64 v[156:157], v[140:141], 0, v[148:149]
	global_store_dwordx4 v[154:155], v[38:41], off offset:512
	global_store_dwordx4 v[156:157], v[30:33], off offset:512
	ds_write_b128 v242, v[22:25]
	ds_write_b128 v242, v[18:21] offset:16
	ds_read_b128 v[22:25], v245
	ds_read_b128 v[18:21], v245 offset:1152
	s_waitcnt lgkmcnt(4)
	v_lshl_add_u64 v[150:151], v[136:137], 0, v[138:139]
	v_lshl_add_u64 v[152:153], v[136:137], 0, v[148:149]
	global_store_dwordx4 v[150:151], v[54:57], off
	global_store_dwordx4 v[152:153], v[50:53], off
	ds_write_b128 v242, v[46:49]
	ds_write_b128 v242, v[42:45] offset:16
	ds_read_b128 v[46:49], v245
	ds_read_b128 v[42:45], v245 offset:1152
	s_waitcnt lgkmcnt(4)
	v_lshl_add_u64 v[154:155], v[136:137], 0, v[138:139]
	v_lshl_add_u64 v[156:157], v[136:137], 0, v[148:149]
	global_store_dwordx4 v[154:155], v[22:25], off offset:512
	global_store_dwordx4 v[156:157], v[18:21], off offset:512
	ds_write_b128 v242, v[14:17]
	ds_write_b128 v242, v[10:13] offset:16
	ds_read_b128 v[14:17], v245
	ds_read_b128 v[10:13], v245 offset:1152
	s_waitcnt lgkmcnt(4)
	v_lshl_add_u64 v[150:151], v[134:135], 0, v[138:139]
	v_lshl_add_u64 v[152:153], v[134:135], 0, v[148:149]
	global_store_dwordx4 v[150:151], v[46:49], off
	global_store_dwordx4 v[152:153], v[42:45], off
	ds_write_b128 v242, v[34:37]
	ds_write_b128 v242, v[26:29] offset:16
	ds_read_b128 v[34:37], v245
	ds_read_b128 v[26:29], v245 offset:1152
	s_waitcnt lgkmcnt(4)
	v_lshl_add_u64 v[154:155], v[134:135], 0, v[138:139]
	v_lshl_add_u64 v[156:157], v[134:135], 0, v[148:149]
	global_store_dwordx4 v[154:155], v[14:17], off offset:512
	global_store_dwordx4 v[156:157], v[10:13], off offset:512
	ds_write_b128 v242, v[6:9]
	ds_write_b128 v242, v[2:5] offset:16
	ds_read_b128 v[6:9], v245
	ds_read_b128 v[2:5], v245 offset:1152
	s_waitcnt lgkmcnt(4)
	v_lshl_add_u64 v[150:151], v[132:133], 0, v[138:139]
	v_lshl_add_u64 v[152:153], v[132:133], 0, v[148:149]
	global_store_dwordx4 v[150:151], v[34:37], off
	global_store_dwordx4 v[152:153], v[26:29], off
	s_waitcnt lgkmcnt(0)
	v_lshl_add_u64 v[154:155], v[132:133], 0, v[138:139]
	v_lshl_add_u64 v[156:157], v[132:133], 0, v[148:149]
	global_store_dwordx4 v[154:155], v[6:9], off offset:512
	global_store_dwordx4 v[156:157], v[2:5], off offset:512
	s_waitcnt vmcnt(0)
	s_barrier
	v_writelane_b32 v253, s0, 8
	v_writelane_b32 v253, s1, 9
	v_writelane_b32 v253, s3, 10
	v_writelane_b32 v253, s18, 11
	v_writelane_b32 v253, s19, 12
	v_writelane_b32 v253, s20, 13
	v_writelane_b32 v253, s21, 14
	v_writelane_b32 v253, s23, 15
	v_lshrrev_b32_e32 v168, 3, v0
	v_lshlrev_b32_e32 v169, 4, v0
	v_bfe_u32 v171, v0, 4, 2
	v_bfe_u32 v2, v0, 3, 25
	v_bfe_u32 v175, v0, 2, 4
	v_bfe_u32 v179, v0, 2, 2
	v_and_b32_e32 v182, 32, v0
	v_and_b32_e32 v172, 64, v0
	v_lshrrev_b32_e32 v180, 1, v0
	v_lshrrev_b32_e32 v181, 5, v0
	v_or_b32_e32 v178, 64, v2
	v_and_b32_e32 v170, 15, v0
	v_lshlrev_b32_e32 v173, 3, v171
	v_lshlrev_b32_e32 v174, 4, v171
	v_lshlrev_b32_e32 v176, 6, v0
	v_lshlrev_b32_e32 v177, 2, v0
	s_add_u32 s12, s28, 0x1f500000
	s_addc_u32 s13, s29, 0
	v_bitop3_b32 v159, v169, v182, 48 bitop3:0x6c
	v_or_b32_e32 v2, v159, v172
	v_and_b32_e32 v156, 24, v180
	v_and_b32_e32 v3, 4, v181
	v_and_or_b32 v4, v168, 48, v175
	v_lshrrev_b32_e32 v2, 1, v2
	v_or3_b32 v3, v3, v179, v156
	v_mul_u32_u24_e32 v160, 0xb00, v4
	v_and_or_b32 v5, v168, 32, v3
	v_or_b32_e32 v4, v2, v160
	s_add_u32 s3, s28, 0x3000000
	v_lshlrev_b32_e32 v130, 1, v4
	v_mul_u32_u24_e32 v4, 0xb00, v5
	s_addc_u32 s35, s29, 0
	v_or_b32_e32 v4, v4, v2
	s_movk_i32 s0, 0x70
	s_add_u32 s8, s28, 0x9a00000
	v_lshlrev_b32_e32 v132, 1, v4
	v_and_or_b32 v4, v178, s0, v175
	s_movk_i32 s0, 0x60
	s_addc_u32 s9, s29, 0
	v_and_or_b32 v3, v178, s0, v3
	s_add_u32 s10, s28, 0x90000
	v_mul_u32_u24_e32 v161, 0xb00, v4
	v_mul_u32_u24_e32 v3, 0xb00, v3
	s_addc_u32 s11, s29, 0
	v_or_b32_e32 v4, v161, v2
	v_or_b32_e32 v2, v3, v2
	v_and_b32_e32 v158, 0x3c0, v176
	v_and_b32_e32 v157, 32, v177
	v_lshlrev_b32_e32 v134, 1, v4
	v_lshlrev_b32_e32 v136, 1, v2
	v_bitop3_b32 v162, v174, v157, v158 bitop3:0x36
	v_readfirstlane_b32 s6, v0
	s_nop 4
	s_branch .Lp13_r1
